# workgroups 128..255 (no S1 tile, idle before the post-attention barrier) touch this layer's S3 B region (48 MB, nt dword per 64 B) so the S3 K loop hits the memory-side cache; on top of v112
# speedup vs baseline: 1.0150x; 1.0000x over previous
; __device__ __forceinline__ KArgsPtr kargs() { KArgsPtr p = (KArgsPtr)__builtin_amdgcn_kernarg_segment_ptr(); asm volatile("" : "+s"(p)); return p; }
; #define GSYNC() do { XSYNC1(); if (PROBE_SYNC) XSYNC1(); } while (0)
; __global__ void __launch_bounds__(512, 2) fwd_megakernel(Args a_unused) {
;     ...
;           for (int un = vcu; un < NB * NHEAD * 16; un += G) { const int bh = un >> 4, qb = un & 15; attn_unit(lds, PROJ, OCAT, subg, lam, 1.0f - lam_init, bh >> 3, bh & 7, qb); } }
;         GSYNC();
;         { KArgsPtr ap = kargs();
;           const int vcu = (G % 8 == 0) ? (bx % 8) * (G / 8) + bx / 8 : bx;
;           pg8::GroupOrder S; S.init(NGRP, 2, 2, G, vcu, WSP(bf16_t, WS_ACOMB), WSP(bf16_t, WS_WCAT) + layer * WCAT_L, KA, KA, (size_t)RG * KA * 2, (size_t)512 * KA * 2);
;           EpiS3 E{WSP(bf16_t, WS_YG)};
;           pg8::gemm_phase(lds, KA, KA, KA, S, E);
.LBB0_473:
	s_cmpk_lt_u32 s75, 0x80
	s_cbranch_scc1 .Ls3b_prefetch_done
	s_load_dwordx2 s[4:5], s[0:1], 0xc8
	s_sub_i32 s8, s75, 0x80
	s_mul_i32 s8, s8, 0x60000
	s_mul_i32 s9, s80, 0x3000000
	s_add_i32 s8, s8, s9
	s_add_i32 s8, s8, 0x4a00000
	v_lshlrev_b32_e32 v0, 6, v234
	s_waitcnt lgkmcnt(0)
	s_add_u32 s4, s4, s8
	s_addc_u32 s5, s5, 0
	global_load_dword v1, v0, s[4:5] nt
	v_add_u32_e32 v0, 0x8000, v0
	global_load_dword v1, v0, s[4:5] nt
	v_add_u32_e32 v0, 0x8000, v0
	global_load_dword v1, v0, s[4:5] nt
	v_add_u32_e32 v0, 0x8000, v0
	global_load_dword v1, v0, s[4:5] nt
	v_add_u32_e32 v0, 0x8000, v0
	global_load_dword v1, v0, s[4:5] nt
	v_add_u32_e32 v0, 0x8000, v0
	global_load_dword v1, v0, s[4:5] nt
	v_add_u32_e32 v0, 0x8000, v0
	global_load_dword v1, v0, s[4:5] nt
	v_add_u32_e32 v0, 0x8000, v0
	global_load_dword v1, v0, s[4:5] nt
	v_add_u32_e32 v0, 0x8000, v0
	global_load_dword v1, v0, s[4:5] nt
	v_add_u32_e32 v0, 0x8000, v0
	global_load_dword v1, v0, s[4:5] nt
	v_add_u32_e32 v0, 0x8000, v0
	global_load_dword v1, v0, s[4:5] nt
	v_add_u32_e32 v0, 0x8000, v0
	global_load_dword v1, v0, s[4:5] nt
